# prep phase conv loop: element index = (wave*gridDim + block)*64 + lane, so the 110592 work items cover 6.75 waves of every workgroup instead of all 8 waves of workgroups 0-215
# baseline (speedup 1.0000x reference)
; __device__ __forceinline__ float silu_(float x) { return x * sigmoid_(x); }
; __device__ __forceinline__ unsigned pk2(float lo, float hi) { return f2bf(lo) | (f2bf(hi) << 16); }
; __device__ __forceinline__ f32x4 ld_bf4(const bf16* p) { const u32x2 w = *(const u32x2*)p; return (f32x4){__builtin_bit_cast(float, w.x << 16), __builtin_bit_cast(float, w.x & 0xffff0000u), __builtin_bit_cast(float, w.y << 16), __builtin_bit_cast(float, w.y & 0xffff0000u)}; }
; __device__ __forceinline__ int bid_() { int t = blockIdx.x; asm volatile("" : "+s"(t)); return t; }
; __device__ __forceinline__ void prep_phase(const Params& P, float* L, int l) {
;     ...
;     { const float* cw = P.ssd_conv_w + (size_t)l * 4 * 768; const float* cb = P.ssd_conv_b + (size_t)l * 768;
;       for (int idx = bid_() * 512 + tid; idx < (MALL / 16) * 192; idx += gridDim.x * 512) {
;           const int chunk = idx / 192, c4 = (idx - chunk * 192) << 2, row0 = chunk * 16;
;           int t0, len; if (row0 < MLAT) { t0 = row0 & (TL - 1); len = TL; } else { t0 = (row0 - MLAT) & (TC - 1); len = TC; }
;           const f32x4 w0 = *(const f32x4*)(cw + c4), w1 = *(const f32x4*)(cw + 768 + c4), w2 = *(const f32x4*)(cw + 2 * 768 + c4), w3 = *(const f32x4*)(cw + 3 * 768 + c4), bb = *(const f32x4*)(cb + c4);
;           const bf16* up = (const bf16*)(P.ws + WS_UG) + (size_t)row0 * NUG + G_SSD_XBC + c4;
;           const f32x4 z4 = {0.f, 0.f, 0.f, 0.f};
;           f32x4 xm1 = (t0 > 0) ? ld_bf4(up - NUG) : z4, x0 = ld_bf4(up), x1 = ld_bf4(up + NUG);
; #pragma unroll
;           for (int r = 0; r < 16; ++r) {
;               const f32x4 x2 = (t0 + r + 2 < len) ? ld_bf4(up + (size_t)(r + 2) * NUG) : z4;
;               f32x4 v = bb + xm1 * w0 + x0 * w1 + x1 * w2 + x2 * w3;
;               v.x = silu_(v.x); v.y = silu_(v.y); v.z = silu_(v.z); v.w = silu_(v.w);
;               { u32x2 w_; w_.x = pk2(v.x, v.y); w_.y = pk2(v.z, v.w); *(u32x2*)(XBC + (size_t)(row0 + r) * 768 + c4) = w_; }
;               xm1 = x0; x0 = x1; x1 = x2;
;           } } }
.LBB0_211:
	v_writelane_b32 v255, s56, 30
	s_movk_i32 s79, 0x800
	s_and_b64 vcc, exec, s[8:9]
	v_writelane_b32 v255, s57, 31
	s_cbranch_vccz .LBB0_252
	v_readlane_b32 s0, v255, 23
	s_cmp_gt_i32 s0, 1
	s_mov_b64 s[6:7], -1
	s_movk_i32 s69, 0x2000
	s_cbranch_scc0 .LBB0_253
	s_cmp_gt_i32 s0, 2
	s_cbranch_scc0 .LBB0_254
	s_cmp_gt_i32 s0, 3
	s_mov_b64 s[0:1], -1
	s_cbranch_scc0 .LBB0_279
	v_readlane_b32 s0, v255, 14
	v_readlane_b32 s1, v255, 15
	s_ashr_i32 s1, s0, 31
	v_mov_b32_e32 v0, v168
	v_writelane_b32 v255, s0, 14
	s_mov_b32 s6, s2
	s_nop 0
	v_writelane_b32 v255, s1, 15
	v_readlane_b32 s98, v254, 18
	v_readlane_b32 s99, v254, 19
	s_load_dword s98, s[98:99], 0x0
	v_lshrrev_b32_e32 v1, 6, v0
	s_waitcnt lgkmcnt(0)
	s_lshl_b32 s98, s98, 6
	v_mul_lo_u32 v1, v1, s98
	v_lshl_add_u32 v1, s6, 6, v1
	v_add_u32_e32 v1, v1, v174
	s_mov_b32 s0, 0x1b000
	v_cmp_gt_i32_e32 vcc, s0, v1
	v_lshlrev_b32_e32 v52, 2, v0
	s_and_saveexec_b64 s[0:1], vcc
	s_cbranch_execz .LBB0_255
	s_add_u32 s4, s94, 0x2ec00000
	v_readlane_b32 s10, v255, 14
	v_readlane_b32 s16, v254, 36
	s_addc_u32 s5, s95, 0
	s_mul_i32 s8, s10, 0x3000
	v_readlane_b32 s26, v254, 46
	s_mul_hi_i32 s7, s10, 0x3000
	v_readlane_b32 s27, v254, 47
	s_add_u32 s8, s26, s8
	v_readlane_b32 s28, v254, 48
	s_addc_u32 s9, s27, s7
	s_mul_hi_i32 s7, s10, 0xc00
	s_mulk_i32 s10, 0xc00
	v_readlane_b32 s12, v254, 18
	v_readlane_b32 s11, v255, 15
	v_readlane_b32 s29, v254, 49
	s_add_u32 s10, s28, s10
	v_readlane_b32 s13, v254, 19
	s_addc_u32 s11, s29, s7
	s_load_dword s7, s[12:13], 0x0
	s_add_u32 s12, s8, 0x1800
	s_addc_u32 s13, s9, 0
	v_readlane_b32 s17, v254, 37
	v_readlane_b32 s18, v254, 38
	v_readlane_b32 s19, v254, 39
	v_readlane_b32 s22, v254, 42
	v_readlane_b32 s23, v254, 43
	s_add_u32 s16, s8, 0x2400
	v_lshlrev_b32_e32 v2, 2, v1
	s_addc_u32 s17, s9, 0
	s_waitcnt lgkmcnt(0)
	s_lshl_b32 s22, s7, 9
	s_nop 0
	s_lshl_b32 s23, s7, 11
	s_mov_b64 s[18:19], 0
	v_readlane_b32 s20, v254, 40
	v_readlane_b32 s21, v254, 41
	v_readlane_b32 s24, v254, 44
	v_readlane_b32 s25, v254, 45
	v_readlane_b32 s30, v254, 50
	v_readlane_b32 s31, v254, 51
	s_branch .LBB0_218
